# RQK: selected-branch QK fragment reads ordered first-needed-first (first MFMA waits for one read instead of two), on v137
# speedup vs baseline: 1.0010x; 1.0002x over previous
.LBB0_909:
	s_cmp_gt_i32 s15, s14
	s_waitcnt lgkmcnt(0)
	s_barrier
	s_cbranch_scc1 .Ld5s_inactive
	s_lshr_b32 s1, s16, 3
	s_and_b32 s1, s1, 0x1ffffffc
	v_add_u32_e32 v50, s1, v114
	ds_read_b32 v50, v50
	s_and_b32 s1, s16, 31
	s_waitcnt lgkmcnt(0)
	v_bfe_u32 v51, v50, s1, 1
	v_cmp_ne_u32_e32 vcc, 0, v51
	s_cbranch_vccz .Ld5s_inactive
	s_mul_i32 s22, s0, 0x4a00
	v_add3_u32 v193, s22, v182, v130
	v_lshrrev_b32_e32 v147, s1, v50
	ds_read_b128 v[50:53], v193
	ds_read_b128 v[152:155], v193 offset:32
	ds_read_b128 v[148:151], v193 offset:4608
	ds_read_b128 v[236:239], v193 offset:4640
	ds_read_b128 v[240:243], v193 offset:64
	ds_read_b128 v[244:247], v193 offset:4672
	ds_read_b128 v[248:251], v193 offset:96
	s_add_i32 s23, s15, 63
	v_cmp_le_i32_e32 vcc, s23, v128
	s_waitcnt lgkmcnt(6)
	v_mfma_f32_32x32x16_bf16 v[66:81], v[50:53], v[82:85], v[34:49]
	s_waitcnt lgkmcnt(5)
	v_mfma_f32_32x32x16_bf16 v[66:81], v[152:155], v[86:89], v[66:81]
	ds_read_b128 v[152:155], v193 offset:4704
	v_and_b32_e32 v147, 1, v147
	s_cmp_lg_u64 vcc, exec
	s_mov_b64 s[0:1], -1
	v_cmp_eq_u32_e32 vcc, 1, v147
	s_mov_b64 s[4:5], -1
	s_waitcnt lgkmcnt(5)
	v_mfma_f32_32x32x16_bf16 v[50:65], v[148:151], v[82:85], v[34:49]
	s_waitcnt lgkmcnt(4)
	v_mfma_f32_32x32x16_bf16 v[50:65], v[236:239], v[86:89], v[50:65]
	s_waitcnt lgkmcnt(3)
	v_mfma_f32_32x32x16_bf16 v[66:81], v[240:243], v[90:93], v[66:81]
	s_waitcnt lgkmcnt(2)
	v_mfma_f32_32x32x16_bf16 v[50:65], v[244:247], v[90:93], v[50:65]
	s_waitcnt lgkmcnt(1)
	v_mfma_f32_32x32x16_bf16 v[66:81], v[248:251], v[94:97], v[66:81]
	s_waitcnt lgkmcnt(0)
	v_mfma_f32_32x32x16_bf16 v[50:65], v[152:155], v[94:97], v[50:65]
	s_cbranch_scc0 .LBB0_917
	v_cndmask_b32_e32 v148, -1, v128, vcc
	v_cmp_le_i32_e32 vcc, s23, v148
	s_cmp_eq_u64 vcc, exec
	s_cbranch_scc1 .LBB0_916
	v_add_u32_e32 v149, s15, v125
	v_cmp_lt_i32_e32 vcc, v149, v148
	v_add_u32_e32 v150, 2, v149
	s_nop 2
	v_cndmask_b32_e32 v67, v169, v67, vcc
	v_cmp_le_i32_e32 vcc, v149, v148
	s_nop 1
	v_cndmask_b32_e32 v66, v169, v66, vcc
	v_cmp_le_i32_e32 vcc, v150, v148
	v_add_u32_e32 v150, 3, v149
	s_nop 0
	v_cndmask_b32_e32 v68, v169, v68, vcc
	v_cmp_le_i32_e32 vcc, v150, v148
	v_add_u32_e32 v150, 8, v149
	s_nop 0
	v_cndmask_b32_e32 v69, v169, v69, vcc
	v_cmp_le_i32_e32 vcc, v150, v148
	v_add_u32_e32 v150, 9, v149
	s_nop 0
	v_cndmask_b32_e32 v70, v169, v70, vcc
	v_cmp_le_i32_e32 vcc, v150, v148
	v_add_u32_e32 v150, 10, v149
	s_nop 0
	v_cndmask_b32_e32 v71, v169, v71, vcc
	v_cmp_le_i32_e32 vcc, v150, v148
	v_add_u32_e32 v150, 11, v149
	s_nop 0
	v_cndmask_b32_e32 v72, v169, v72, vcc
	v_cmp_le_i32_e32 vcc, v150, v148
	v_add_u32_e32 v150, 16, v149
	s_nop 0
	v_cndmask_b32_e32 v73, v169, v73, vcc
	v_cmp_le_i32_e32 vcc, v150, v148
	v_add_u32_e32 v150, 17, v149
	s_nop 0
	v_cndmask_b32_e32 v74, v169, v74, vcc
	v_cmp_le_i32_e32 vcc, v150, v148
	v_add_u32_e32 v150, 18, v149
	s_nop 0
	v_cndmask_b32_e32 v75, v169, v75, vcc
	v_cmp_le_i32_e32 vcc, v150, v148
	v_add_u32_e32 v150, 19, v149
	s_nop 0
	v_cndmask_b32_e32 v76, v169, v76, vcc
	v_cmp_le_i32_e32 vcc, v150, v148
	v_add_u32_e32 v150, 24, v149
	s_nop 0
	v_cndmask_b32_e32 v77, v169, v77, vcc
	v_cmp_le_i32_e32 vcc, v150, v148
	v_add_u32_e32 v150, 25, v149
	s_nop 0
	v_cndmask_b32_e32 v78, v169, v78, vcc
	v_cmp_le_i32_e32 vcc, v150, v148
	v_add_u32_e32 v150, 26, v149
	s_nop 0
	v_cndmask_b32_e32 v79, v169, v79, vcc
	v_cmp_le_i32_e32 vcc, v150, v148
	v_add_u32_e32 v150, 27, v149
	s_nop 0
	v_cndmask_b32_e32 v80, v169, v80, vcc
	v_cmp_le_i32_e32 vcc, v150, v148
	v_add_u32_e32 v150, 32, v149
	s_nop 0
	v_cndmask_b32_e32 v81, v169, v81, vcc
	v_cmp_le_i32_e32 vcc, v150, v148
	v_add_u32_e32 v150, 33, v149
	s_nop 0
	v_cndmask_b32_e32 v50, v169, v50, vcc
	v_cmp_le_i32_e32 vcc, v150, v148
	v_add_u32_e32 v150, 34, v149
	s_nop 0
	v_cndmask_b32_e32 v51, v169, v51, vcc
	v_cmp_le_i32_e32 vcc, v150, v148
	v_add_u32_e32 v150, 35, v149
	s_nop 0
	v_cndmask_b32_e32 v52, v169, v52, vcc
	v_cmp_le_i32_e32 vcc, v150, v148
	v_add_u32_e32 v150, 40, v149
	s_nop 0
	v_cndmask_b32_e32 v53, v169, v53, vcc
	v_cmp_le_i32_e32 vcc, v150, v148
	v_add_u32_e32 v150, 41, v149
	s_nop 0
	v_cndmask_b32_e32 v54, v169, v54, vcc
	v_cmp_le_i32_e32 vcc, v150, v148
	v_add_u32_e32 v150, 42, v149
	s_nop 0
	v_cndmask_b32_e32 v55, v169, v55, vcc
	v_cmp_le_i32_e32 vcc, v150, v148
	v_add_u32_e32 v150, 43, v149
	s_nop 0
	v_cndmask_b32_e32 v56, v169, v56, vcc
	v_cmp_le_i32_e32 vcc, v150, v148
	v_add_u32_e32 v150, 48, v149
	s_nop 0
	v_cndmask_b32_e32 v57, v169, v57, vcc
	v_cmp_le_i32_e32 vcc, v150, v148
	v_add_u32_e32 v150, 49, v149
	s_nop 0
	v_cndmask_b32_e32 v58, v169, v58, vcc
	v_cmp_le_i32_e32 vcc, v150, v148
	v_add_u32_e32 v150, 50, v149
	s_nop 0
	v_cndmask_b32_e32 v59, v169, v59, vcc
	v_cmp_le_i32_e32 vcc, v150, v148
	v_add_u32_e32 v150, 51, v149
	s_nop 0
	v_cndmask_b32_e32 v60, v169, v60, vcc
	v_cmp_le_i32_e32 vcc, v150, v148
	v_add_u32_e32 v150, 56, v149
	s_nop 0
	v_cndmask_b32_e32 v61, v169, v61, vcc
	v_cmp_le_i32_e32 vcc, v150, v148
	v_add_u32_e32 v150, 57, v149
	s_nop 0
	v_cndmask_b32_e32 v62, v169, v62, vcc
	v_cmp_le_i32_e32 vcc, v150, v148
	v_add_u32_e32 v150, 58, v149
	v_add_u32_e32 v149, 59, v149
	v_cndmask_b32_e32 v63, v169, v63, vcc
	v_cmp_le_i32_e32 vcc, v150, v148
	s_nop 1
	v_cndmask_b32_e32 v64, v169, v64, vcc
	v_cmp_gt_i32_e32 vcc, v149, v148
	s_and_saveexec_b64 s[4:5], vcc
	v_mov_b32_e32 v65, 0xf149f2ca
	s_or_b64 exec, exec, s[4:5]
